# prologue silu(c) loop flattened: 12 loads issued together instead of 12 dependent load-compute iterations
# speedup vs baseline: 1.0069x; 1.0069x over previous
; DI void phase_prologue(const Frame& F0, const Args& a) {
;     ...
;         for (int i = F.tid; i < 3 * DM; i += 512) { const int mb = i / DM, k = i % DM; const float cv = mb < 2 ? a.c[mb * DM + k] : a.c_ctx[k]; sv[i] = cv / (1.0f + __expf(-cv)); }
.LBB0_12:
	v_mov_b32_e32 v1, v0
	s_mov_b32 s44, s50
	v_mov_b32_e32 v78, v222
	v_readlane_b32 s60, v252, 48
	v_readlane_b32 s86, v252, 46
	s_movk_i32 s0, 0x1800
	v_readlane_b32 s87, v252, 47
	v_cmp_gt_i32_e32 vcc, s0, v1
	s_and_saveexec_b64 s[0:1], vcc
	s_cbranch_execz .LBB0_19
; DI void phase_prologue(const Frame& F0, const Args& a) {
;     ...
;         for (int i = F.tid; i < 3 * DM; i += 512) { const int mb = i / DM, k = i % DM; const float cv = mb < 2 ? a.c[mb * DM + k] : a.c_ctx[k]; sv[i] = cv / (1.0f + __expf(-cv)); }
	v_readlane_b32 s10, v252, 10
	v_readlane_b32 s11, v252, 11
	v_readlane_b32 s20, v252, 14
	v_readlane_b32 s21, v252, 15
	v_lshlrev_b32_e32 v4, 2, v1
	v_add_u32_e32 v11, 0x1000, v4
	v_add_u32_e32 v12, 0x2000, v4
	v_add_u32_e32 v13, 0x3000, v4
	v_and_b32_e32 v14, 7, v1
	v_lshrrev_b32_e32 v15, 3, v1
	v_lshlrev_b32_e32 v14, 10, v14
	v_lshl_add_u32 v14, v15, 2, v14
	global_load_dword v20, v4, s[10:11]
	global_load_dword v21, v4, s[10:11] offset:2048
	global_load_dword v22, v11, s[10:11]
	global_load_dword v23, v11, s[10:11] offset:2048
	global_load_dword v24, v12, s[10:11]
	global_load_dword v25, v12, s[10:11] offset:2048
	global_load_dword v26, v13, s[10:11]
	global_load_dword v27, v13, s[10:11] offset:2048
	global_load_dword v28, v4, s[20:21]
	global_load_dword v29, v4, s[20:21] offset:2048
	global_load_dword v30, v11, s[20:21]
	global_load_dword v31, v11, s[20:21] offset:2048
	s_waitcnt vmcnt(11)
	v_mov_b32_e32 v2, v20
	v_mul_f32_e32 v3, 0xbfb8aa3b, v2
	v_exp_f32_e32 v3, v3
	s_nop 0
	v_add_f32_e32 v3, 1.0, v3
	v_div_scale_f32 v5, s[6:7], v3, v3, v2
	v_rcp_f32_e32 v7, v5
	v_div_scale_f32 v8, vcc, v2, v3, v2
	v_fma_f32 v9, -v5, v7, 1.0
	v_fmac_f32_e32 v7, v9, v7
	v_mul_f32_e32 v9, v8, v7
	v_fma_f32 v10, -v5, v9, v8
	v_fmac_f32_e32 v9, v10, v7
	v_fma_f32 v5, -v5, v9, v8
	v_div_fmas_f32 v5, v5, v7, v9
	v_div_fixup_f32 v2, v5, v3, v2
	ds_write_b32 v14, v2
	s_waitcnt vmcnt(10)
	v_mov_b32_e32 v2, v21
	v_mul_f32_e32 v3, 0xbfb8aa3b, v2
	v_exp_f32_e32 v3, v3
	s_nop 0
	v_add_f32_e32 v3, 1.0, v3
	v_div_scale_f32 v5, s[6:7], v3, v3, v2
	v_rcp_f32_e32 v7, v5
	v_div_scale_f32 v8, vcc, v2, v3, v2
	v_fma_f32 v9, -v5, v7, 1.0
	v_fmac_f32_e32 v7, v9, v7
	v_mul_f32_e32 v9, v8, v7
	v_fma_f32 v10, -v5, v9, v8
	v_fmac_f32_e32 v9, v10, v7
	v_fma_f32 v5, -v5, v9, v8
	v_div_fmas_f32 v5, v5, v7, v9
	v_div_fixup_f32 v2, v5, v3, v2
	ds_write_b32 v14, v2 offset:256
	s_waitcnt vmcnt(9)
	v_mov_b32_e32 v2, v22
	v_mul_f32_e32 v3, 0xbfb8aa3b, v2
	v_exp_f32_e32 v3, v3
	s_nop 0
	v_add_f32_e32 v3, 1.0, v3
	v_div_scale_f32 v5, s[6:7], v3, v3, v2
	v_rcp_f32_e32 v7, v5
	v_div_scale_f32 v8, vcc, v2, v3, v2
	v_fma_f32 v9, -v5, v7, 1.0
	v_fmac_f32_e32 v7, v9, v7
	v_mul_f32_e32 v9, v8, v7
	v_fma_f32 v10, -v5, v9, v8
	v_fmac_f32_e32 v9, v10, v7
	v_fma_f32 v5, -v5, v9, v8
	v_div_fmas_f32 v5, v5, v7, v9
	v_div_fixup_f32 v2, v5, v3, v2
	ds_write_b32 v14, v2 offset:512
	s_waitcnt vmcnt(8)
	v_mov_b32_e32 v2, v23
	v_mul_f32_e32 v3, 0xbfb8aa3b, v2
	v_exp_f32_e32 v3, v3
	s_nop 0
	v_add_f32_e32 v3, 1.0, v3
	v_div_scale_f32 v5, s[6:7], v3, v3, v2
	v_rcp_f32_e32 v7, v5
	v_div_scale_f32 v8, vcc, v2, v3, v2
	v_fma_f32 v9, -v5, v7, 1.0
	v_fmac_f32_e32 v7, v9, v7
	v_mul_f32_e32 v9, v8, v7
	v_fma_f32 v10, -v5, v9, v8
	v_fmac_f32_e32 v9, v10, v7
	v_fma_f32 v5, -v5, v9, v8
	v_div_fmas_f32 v5, v5, v7, v9
	v_div_fixup_f32 v2, v5, v3, v2
	ds_write_b32 v14, v2 offset:768
	s_waitcnt vmcnt(7)
	v_mov_b32_e32 v2, v24
	v_mul_f32_e32 v3, 0xbfb8aa3b, v2
	v_exp_f32_e32 v3, v3
	s_nop 0
	v_add_f32_e32 v3, 1.0, v3
	v_div_scale_f32 v5, s[6:7], v3, v3, v2
	v_rcp_f32_e32 v7, v5
	v_div_scale_f32 v8, vcc, v2, v3, v2
	v_fma_f32 v9, -v5, v7, 1.0
	v_fmac_f32_e32 v7, v9, v7
	v_mul_f32_e32 v9, v8, v7
	v_fma_f32 v10, -v5, v9, v8
	v_fmac_f32_e32 v9, v10, v7
	v_fma_f32 v5, -v5, v9, v8
	v_div_fmas_f32 v5, v5, v7, v9
	v_div_fixup_f32 v2, v5, v3, v2
	ds_write_b32 v14, v2 offset:8192
	s_waitcnt vmcnt(6)
	v_mov_b32_e32 v2, v25
	v_mul_f32_e32 v3, 0xbfb8aa3b, v2
	v_exp_f32_e32 v3, v3
	s_nop 0
	v_add_f32_e32 v3, 1.0, v3
	v_div_scale_f32 v5, s[6:7], v3, v3, v2
	v_rcp_f32_e32 v7, v5
	v_div_scale_f32 v8, vcc, v2, v3, v2
	v_fma_f32 v9, -v5, v7, 1.0
	v_fmac_f32_e32 v7, v9, v7
	v_mul_f32_e32 v9, v8, v7
	v_fma_f32 v10, -v5, v9, v8
	v_fmac_f32_e32 v9, v10, v7
	v_fma_f32 v5, -v5, v9, v8
	v_div_fmas_f32 v5, v5, v7, v9
	v_div_fixup_f32 v2, v5, v3, v2
	ds_write_b32 v14, v2 offset:8448
	s_waitcnt vmcnt(5)
	v_mov_b32_e32 v2, v26
	v_mul_f32_e32 v3, 0xbfb8aa3b, v2
	v_exp_f32_e32 v3, v3
	s_nop 0
	v_add_f32_e32 v3, 1.0, v3
	v_div_scale_f32 v5, s[6:7], v3, v3, v2
	v_rcp_f32_e32 v7, v5
	v_div_scale_f32 v8, vcc, v2, v3, v2
	v_fma_f32 v9, -v5, v7, 1.0
	v_fmac_f32_e32 v7, v9, v7
	v_mul_f32_e32 v9, v8, v7
	v_fma_f32 v10, -v5, v9, v8
	v_fmac_f32_e32 v9, v10, v7
	v_fma_f32 v5, -v5, v9, v8
	v_div_fmas_f32 v5, v5, v7, v9
	v_div_fixup_f32 v2, v5, v3, v2
	ds_write_b32 v14, v2 offset:8704
	s_waitcnt vmcnt(4)
	v_mov_b32_e32 v2, v27
	v_mul_f32_e32 v3, 0xbfb8aa3b, v2
	v_exp_f32_e32 v3, v3
	s_nop 0
	v_add_f32_e32 v3, 1.0, v3
	v_div_scale_f32 v5, s[6:7], v3, v3, v2
	v_rcp_f32_e32 v7, v5
	v_div_scale_f32 v8, vcc, v2, v3, v2
	v_fma_f32 v9, -v5, v7, 1.0
	v_fmac_f32_e32 v7, v9, v7
	v_mul_f32_e32 v9, v8, v7
	v_fma_f32 v10, -v5, v9, v8
	v_fmac_f32_e32 v9, v10, v7
	v_fma_f32 v5, -v5, v9, v8
	v_div_fmas_f32 v5, v5, v7, v9
	v_div_fixup_f32 v2, v5, v3, v2
	ds_write_b32 v14, v2 offset:8960
	s_waitcnt vmcnt(3)
	v_mov_b32_e32 v2, v28
	v_mul_f32_e32 v3, 0xbfb8aa3b, v2
	v_exp_f32_e32 v3, v3
	s_nop 0
	v_add_f32_e32 v3, 1.0, v3
	v_div_scale_f32 v5, s[6:7], v3, v3, v2
	v_rcp_f32_e32 v7, v5
	v_div_scale_f32 v8, vcc, v2, v3, v2
	v_fma_f32 v9, -v5, v7, 1.0
	v_fmac_f32_e32 v7, v9, v7
	v_mul_f32_e32 v9, v8, v7
	v_fma_f32 v10, -v5, v9, v8
	v_fmac_f32_e32 v9, v10, v7
	v_fma_f32 v5, -v5, v9, v8
	v_div_fmas_f32 v5, v5, v7, v9
	v_div_fixup_f32 v2, v5, v3, v2
	ds_write_b32 v14, v2 offset:16384
	s_waitcnt vmcnt(2)
	v_mov_b32_e32 v2, v29
	v_mul_f32_e32 v3, 0xbfb8aa3b, v2
	v_exp_f32_e32 v3, v3
	s_nop 0
	v_add_f32_e32 v3, 1.0, v3
	v_div_scale_f32 v5, s[6:7], v3, v3, v2
	v_rcp_f32_e32 v7, v5
	v_div_scale_f32 v8, vcc, v2, v3, v2
	v_fma_f32 v9, -v5, v7, 1.0
	v_fmac_f32_e32 v7, v9, v7
	v_mul_f32_e32 v9, v8, v7
	v_fma_f32 v10, -v5, v9, v8
	v_fmac_f32_e32 v9, v10, v7
	v_fma_f32 v5, -v5, v9, v8
	v_div_fmas_f32 v5, v5, v7, v9
	v_div_fixup_f32 v2, v5, v3, v2
	ds_write_b32 v14, v2 offset:16640
	s_waitcnt vmcnt(1)
	v_mov_b32_e32 v2, v30
	v_mul_f32_e32 v3, 0xbfb8aa3b, v2
	v_exp_f32_e32 v3, v3
	s_nop 0
	v_add_f32_e32 v3, 1.0, v3
	v_div_scale_f32 v5, s[6:7], v3, v3, v2
	v_rcp_f32_e32 v7, v5
	v_div_scale_f32 v8, vcc, v2, v3, v2
	v_fma_f32 v9, -v5, v7, 1.0
	v_fmac_f32_e32 v7, v9, v7
	v_mul_f32_e32 v9, v8, v7
	v_fma_f32 v10, -v5, v9, v8
	v_fmac_f32_e32 v9, v10, v7
	v_fma_f32 v5, -v5, v9, v8
	v_div_fmas_f32 v5, v5, v7, v9
	v_div_fixup_f32 v2, v5, v3, v2
	ds_write_b32 v14, v2 offset:16896
	s_waitcnt vmcnt(0)
	v_mov_b32_e32 v2, v31
	v_mul_f32_e32 v3, 0xbfb8aa3b, v2
	v_exp_f32_e32 v3, v3
	s_nop 0
	v_add_f32_e32 v3, 1.0, v3
	v_div_scale_f32 v5, s[6:7], v3, v3, v2
	v_rcp_f32_e32 v7, v5
	v_div_scale_f32 v8, vcc, v2, v3, v2
	v_fma_f32 v9, -v5, v7, 1.0
	v_fmac_f32_e32 v7, v9, v7
	v_mul_f32_e32 v9, v8, v7
	v_fma_f32 v10, -v5, v9, v8
	v_fmac_f32_e32 v9, v10, v7
	v_fma_f32 v5, -v5, v9, v8
	v_div_fmas_f32 v5, v5, v7, v9
	v_div_fixup_f32 v2, v5, v3, v2
	ds_write_b32 v14, v2 offset:17152
